# v32 + reversed round order (tile index xor 256) in the two K=2816 residual GEMMs so the most recently written activation rows are read first
# baseline (speedup 1.0000x reference)
; __device__ __forceinline__ const float* INP(const Params& p, int i) { asm volatile("" : "+s"(i)); return p.in[i]; }
; __device__ __forceinline__ int BID() { int t = blockIdx.x; asm volatile("" : "+s"(t)); return t; }
; __device__ __forceinline__ int NBLK() { int t = gridDim.x; asm volatile("" : "+s"(t)); return t; }
; __device__ __forceinline__ unsigned char* WSP(const Params& p) { unsigned char* w = p.ws; asm volatile("" : "+s"(w)); return w; }
; __device__ __forceinline__ float* OUTP(const Params& p) { float* w = p.out; asm volatile("" : "+s"(w)); return w; }
; __global__ void __launch_bounds__(512, 2) fwd_kernel(Params p, int ph_lo, int ph_hi) {
;     ...
;         const int G = NBLK(), c = BID();
;         unsigned char* ws = WSP(p); float* xo = OUTP(p);
;         bf16_t* W = (bf16_t*)(ws + WS_W); bf16_t* H = (bf16_t*)(ws + WS_H); bf16_t* ACT = (bf16_t*)(ws + WS_R);
;         if (ph == N_PHASES - 1) { rmsnorm_phase(xo, INP(p, 35), nullptr, xo); }
;         else {
;             const int l = ph / PH_PER_LAYER, k = ph % PH_PER_LAYER;
;             const float* xin = (l == 0) ? INP(p, 0) : xo;
;             switch (k) {
;     ...
;             case 13: if (PHON(13)) { pg8::Gemm g{ACT, W + W_D2, T_, D_, FF_, 0, 0}; pg8::OrderPlain S; S.init(T_, D_, G, c); pg8::EpiRes E{xo, xo, 0.5f}; pg8::gemm_phase(lds, g, S, E); } break;
.LBB0_18:
	s_mul_hi_i32 s2, s68, 0x92492493
	s_add_i32 s2, s2, s68
	s_lshr_b32 s3, s2, 31
	s_ashr_i32 s2, s2, 3
	s_add_i32 s4, s2, s3
	s_mov_b32 s2, s4
	v_writelane_b32 v254, s2, 31
	s_nop 1
	v_writelane_b32 v254, s3, 32
	s_mul_i32 s2, s4, 14
	s_sub_i32 s4, s68, s2
	v_readlane_b32 s6, v254, 25
	v_readlane_b32 s7, v254, 26
	s_add_u32 s2, s6, 0x4700000
	s_addc_u32 s3, s7, 0
	v_writelane_b32 v254, s2, 33
	s_nop 1
	v_writelane_b32 v254, s3, 34
	s_add_u32 s2, s6, 0x8700000
	s_addc_u32 s3, s7, 0
	v_writelane_b32 v254, s2, 35
	s_cmp_lt_i32 s4, 7
	s_nop 0
	v_writelane_b32 v254, s3, 36
	v_writelane_b32 v254, s4, 37
	s_mov_b64 s[2:3], -1
	v_writelane_b32 v254, s68, 38
	s_cbranch_scc1 .LBB0_228
	v_readlane_b32 s2, v254, 37
	s_cmp_lt_i32 s2, 10
	s_mov_b64 s[2:3], -1
	s_cbranch_scc1 .LBB0_114
	v_readlane_b32 s2, v254, 37
	s_cmp_lt_i32 s2, 12
	s_mov_b64 s[2:3], -1
	s_cbranch_scc1 .LBB0_77
	v_readlane_b32 s2, v254, 37
	s_cmp_lt_i32 s2, 13
	s_mov_b64 s[2:3], -1
	s_cbranch_scc1 .LBB0_54
	v_readlane_b32 s2, v254, 37
	s_cmp_eq_u32 s2, 13
	s_cbranch_scc0 .LBB0_53
	s_waitcnt vmcnt(0)
	v_mov_b32_e32 v14, v168
	v_readlane_b32 s3, v254, 24
	s_movk_i32 s2, 0xb00
	v_readfirstlane_b32 s14, v14
	s_cmpk_gt_i32 s3, 0x1ff
	s_cbranch_scc1 .LBB0_53
	v_readlane_b32 s4, v254, 24
	s_xor_b32 s4, s4, 0x100
	s_ashr_i32 s22, s4, 31
	s_lshr_b32 s3, s22, 29
	s_add_i32 s6, s4, s3
	s_and_b32 s3, s6, -8
	s_sub_i32 s3, s4, s3
	s_cmp_gt_i32 s3, -1
	s_mov_b64 s[4:5], -1
	s_cbranch_scc0 .LBB0_26
	s_lshl_b32 s10, s3, 6
	s_mov_b64 s[4:5], 0

;     __device__ __forceinline__ bool next(int i, Unit& u) const { const long L = (long)i * G + c; if (L >= nwg) return false; tile_map((int)L, nM, nN, nwg, u.pm, u.pn); u.z = 0; return true; }
;     __device__ __forceinline__ bool next(int i, Unit& u) const { const long L = (long)(i / 3) * G + c; if (L >= nwg) return false; tile_map((int)L, nM, nN, nwg, u.pm, u.pn); u.z = i % 3; return true; }
;     __device__ __forceinline__ bool next(int i, Unit& u) const { const long L = (long)i * G + c; if (L >= total) return false; u.z = (int)(L / per); const int r = (int)(L % per); u.pm = r % nM; u.pn = r / nM; return true; }
; template <class Epi, class Sched, bool HALFN = false>
; __device__ __forceinline__ void gemm_phase(LAS unsigned char* lds, const Gemm g, const Sched& S, const Epi& E) {
;     ...
;         const bool has_next = S.next(ui + 1, nxt);
.LBB0_33:
	s_add_i32 s55, s55, 1
	s_mul_i32 s2, s55, s54
	s_mul_hi_u32 s3, s55, s53
	s_add_i32 s3, s3, s2
	s_mul_i32 s2, s55, s53
	v_readlane_b32 s4, v254, 24
	s_add_u32 s2, s2, s4
	s_addc_u32 s3, s3, s22
	s_xor_b32 s2, s2, 0x100
	v_cmp_gt_i64_e32 vcc, s[2:3], v[132:133]
	v_cmp_lt_i64_e64 s[4:5], s[2:3], v[130:131]
	s_cbranch_vccnz .LBB0_39
	s_ashr_i32 s3, s2, 31
	s_lshr_b32 s3, s3, 29
	s_add_i32 s16, s2, s3
	s_and_b32 s3, s16, -8
	s_sub_i32 s17, s2, s3
	s_cmp_gt_i32 s17, -1
	s_mov_b64 s[2:3], -1
	s_cbranch_scc0 .LBB0_36
	s_lshl_b32 s56, s17, 6
	s_mov_b64 s[2:3], 0

; __device__ __forceinline__ const float* INP(const Params& p, int i) { asm volatile("" : "+s"(i)); return p.in[i]; }
; __global__ void __launch_bounds__(512, 2) fwd_kernel(Params p, int ph_lo, int ph_hi) {
;     ...
;             switch (k) {
;             case 0: if (PHON(0)) for (int rep = 0; rep < REPS(0); ++rep) { prep_phase(p, l, lds); rmsnorm_phase(xin, INP(p, 1) + (size_t)l * D_, H, nullptr); } break;
;             case 1: if (PHON(1)) for (int rep = 0; rep < REPS(1); ++rep) { pg8::Gemm g{H, W + W_GU1, T_, 5632, D_, 0, 0}; pg8::OrderPlain S; S.init(T_, 5632, G, c); pg8::EpiAct E{ACT}; pg8::gemm_phase(lds, g, S, E); } break;
;             case 2: if (PHON(2)) { pg8::Gemm g{ACT, W + W_D1, T_, D_, FF_, 0, 0}; pg8::OrderPlain S; S.init(T_, D_, G, c); pg8::EpiRes E{xin, xo, 0.5f}; pg8::gemm_phase(lds, g, S, E); } break;
.LBB0_605:
	s_andn2_b64 vcc, exec, s[2:3]
	s_cbranch_vccnz .LBB0_664
	v_readlane_b32 s2, v254, 37
	s_cmp_lt_i32 s2, 1
	s_mov_b64 s[2:3], -1
	s_cbranch_scc1 .LBB0_662
	v_readlane_b32 s2, v254, 37
	s_cmp_gt_i32 s2, 1
	s_mov_b64 s[2:3], -1
	s_cbranch_scc0 .LBB0_639
	s_waitcnt vmcnt(0)
	v_mov_b32_e32 v14, v168
	v_readlane_b32 s3, v254, 24
	s_movk_i32 s2, 0xb00
	v_readfirstlane_b32 s14, v14
	s_cmpk_gt_i32 s3, 0x1ff
	s_cbranch_scc1 .LBB0_638
	v_readlane_b32 s4, v254, 24
	s_xor_b32 s4, s4, 0x100
	s_ashr_i32 s22, s4, 31
	s_lshr_b32 s3, s22, 29
	s_add_i32 s10, s4, s3
	s_and_b32 s3, s10, -8
	s_sub_i32 s3, s4, s3
	s_cmp_gt_i32 s3, -1
	s_mov_b64 s[4:5], -1
	s_cbranch_scc0 .LBB0_611
	s_lshl_b32 s11, s3, 6
	s_mov_b64 s[4:5], 0
